# v37 + s_nop 0 clause breaks between the hoisted K/V load pairs whose second load overwrites the address registers (hipcc's own rule; no functional change)
# speedup vs baseline: 1.0014x; 1.0009x over previous
.LBB0_1067:
	v_ldexp_f32 v11, v11, s7
	v_log_f32_e32 v11, v11
	v_cndmask_b32_e32 v12, 0, v22, vcc
	s_andn2_b64 vcc, exec, s[4:5]
	v_add_u32_e32 v18, v240, v253
	v_sub_f32_e32 v237, v11, v12
	v_add_u32_e32 v17, v240, v254
	v_add_u32_e32 v16, v240, v252
	v_add_u32_e32 v15, v240, v242
	v_add_u32_e32 v14, v240, v241
	v_add_u32_e32 v13, v240, v243
	v_add_u32_e32 v12, v240, v251
	v_add_u32_e32 v11, v240, v250
	s_cbranch_vccnz .LBB0_1069
	s_mov_b32 s7, s81
	s_lshl_b64 s[4:5], s[6:7], 17
	s_add_u32 s4, s19, s4
	s_addc_u32 s5, s22, s5
	s_mov_b64 s[16:17], s[4:5]
	v_add_u32_e32 v20, 0x10800, v29
	v_lshl_add_u64 v[30:31], s[16:17], 0, v[230:231]
	s_add_u32 s16, s4, 0x2000
	s_addc_u32 s17, s5, 0
	global_load_dwordx4 v[30:33], v[30:31], off nt
	s_nop 0
	v_lshl_add_u64 v[34:35], s[16:17], 0, v[230:231]
	s_add_u32 s16, s4, 0x4000
	s_addc_u32 s17, s5, 0
	global_load_dwordx4 v[34:37], v[34:35], off nt
	s_nop 0
	v_lshl_add_u64 v[38:39], s[16:17], 0, v[230:231]
	s_add_u32 s16, s4, 0x6000
	s_addc_u32 s17, s5, 0
	global_load_dwordx4 v[38:41], v[38:39], off nt
	s_nop 0
	v_lshl_add_u64 v[42:43], s[16:17], 0, v[230:231]
	s_add_u32 s16, s4, 0x8000
	s_addc_u32 s17, s5, 0
	global_load_dwordx4 v[42:45], v[42:43], off nt
	s_nop 0
	v_lshl_add_u64 v[46:47], s[16:17], 0, v[230:231]
	s_add_u32 s16, s4, 0xa000
	s_addc_u32 s17, s5, 0
	global_load_dwordx4 v[46:49], v[46:47], off nt
	s_nop 0
	v_lshl_add_u64 v[50:51], s[16:17], 0, v[230:231]
	s_add_u32 s16, s4, 0xc000
	s_addc_u32 s17, s5, 0
	global_load_dwordx4 v[50:53], v[50:51], off nt
	s_nop 0
	v_lshl_add_u64 v[54:55], s[16:17], 0, v[230:231]
	s_add_u32 s16, s4, 0xe000
	s_addc_u32 s17, s5, 0
	global_load_dwordx4 v[54:57], v[54:55], off nt
	s_nop 0
	v_lshl_add_u64 v[58:59], s[16:17], 0, v[230:231]
	s_add_u32 s16, s4, 0x10000
	s_addc_u32 s17, s5, 0
	global_load_dwordx4 v[58:61], v[58:59], off nt
	s_nop 0
	v_lshl_add_u64 v[62:63], s[16:17], 0, v[230:231]
	s_add_u32 s16, s4, 0x12000
	s_addc_u32 s17, s5, 0
	global_load_dwordx4 v[62:65], v[62:63], off nt
	s_nop 0
	v_lshl_add_u64 v[66:67], s[16:17], 0, v[230:231]
	s_add_u32 s16, s4, 0x14000
	s_addc_u32 s17, s5, 0
	global_load_dwordx4 v[66:69], v[66:67], off nt
	s_nop 0
	v_lshl_add_u64 v[70:71], s[16:17], 0, v[230:231]
	s_add_u32 s16, s4, 0x16000
	s_addc_u32 s17, s5, 0
	global_load_dwordx4 v[70:73], v[70:71], off nt
	s_nop 0
	v_lshl_add_u64 v[74:75], s[16:17], 0, v[230:231]
	s_add_u32 s16, s4, 0x18000
	s_addc_u32 s17, s5, 0
	global_load_dwordx4 v[74:77], v[74:75], off nt
	s_nop 0
	v_lshl_add_u64 v[78:79], s[16:17], 0, v[230:231]
	s_add_u32 s16, s4, 0x1a000
	s_addc_u32 s17, s5, 0
	global_load_dwordx4 v[78:81], v[78:79], off nt
	s_nop 0
	v_lshl_add_u64 v[82:83], s[16:17], 0, v[230:231]
	s_add_u32 s16, s4, 0x1c000
	s_addc_u32 s17, s5, 0
	s_add_u32 s4, s4, 0x1e000
	global_load_dwordx4 v[82:85], v[82:83], off nt
	s_addc_u32 s5, s5, 0
	v_lshl_add_u64 v[86:87], s[16:17], 0, v[230:231]
	global_load_dwordx4 v[86:89], v[86:87], off nt
	s_nop 0
	v_lshl_add_u64 v[90:91], s[4:5], 0, v[230:231]
	global_load_dwordx4 v[90:93], v[90:91], off nt
	s_mul_hi_u32 s4, s13, 0x2a00
	s_add_u32 s5, s10, s14
	s_addc_u32 s4, s11, s4
	s_lshl_b32 s7, s12, 1
	s_add_u32 s7, s5, s7
	s_addc_u32 s13, s4, 0
	s_add_u32 s4, s7, 0x1200
	s_addc_u32 s5, s13, 0
	v_lshl_add_u64 v[130:131], s[4:5], 0, v[234:235]
	s_add_u32 s4, s7, 0x2b200
	s_addc_u32 s5, s13, 0
	global_load_dwordx4 v[126:129], v[130:131], off nt
	s_nop 0
	global_load_dwordx4 v[130:133], v[130:131], off offset:2048 nt
	v_lshl_add_u64 v[138:139], s[4:5], 0, v[234:235]
	s_add_u32 s4, s7, 0x55200
	s_addc_u32 s5, s13, 0
	global_load_dwordx4 v[134:137], v[138:139], off nt
	s_nop 0
	global_load_dwordx4 v[138:141], v[138:139], off offset:2048 nt
	v_lshl_add_u64 v[146:147], s[4:5], 0, v[234:235]
	s_add_u32 s4, s7, 0x7f200
	s_addc_u32 s5, s13, 0
	global_load_dwordx4 v[142:145], v[146:147], off nt
	s_nop 0
	global_load_dwordx4 v[146:149], v[146:147], off offset:2048 nt
	v_lshl_add_u64 v[154:155], s[4:5], 0, v[234:235]
	s_add_u32 s4, s7, 0xa9200
	s_addc_u32 s5, s13, 0
	global_load_dwordx4 v[150:153], v[154:155], off nt
	s_nop 0
	global_load_dwordx4 v[154:157], v[154:155], off offset:2048 nt
	v_lshl_add_u64 v[162:163], s[4:5], 0, v[234:235]
	s_add_u32 s4, s7, 0xd3200
	s_addc_u32 s5, s13, 0
	global_load_dwordx4 v[158:161], v[162:163], off nt
	s_nop 0
	global_load_dwordx4 v[162:165], v[162:163], off offset:2048 nt
	v_lshl_add_u64 v[170:171], s[4:5], 0, v[234:235]
	s_add_u32 s4, s7, 0xfd200
	s_addc_u32 s5, s13, 0
	global_load_dwordx4 v[166:169], v[170:171], off nt
	s_nop 0
	global_load_dwordx4 v[170:173], v[170:171], off offset:2048 nt
	v_lshl_add_u64 v[178:179], s[4:5], 0, v[234:235]
	s_add_u32 s4, s7, 0x127200
	s_addc_u32 s5, s13, 0
	global_load_dwordx4 v[174:177], v[178:179], off nt
	s_nop 0
	global_load_dwordx4 v[178:181], v[178:179], off offset:2048 nt
	v_lshl_add_u64 v[186:187], s[4:5], 0, v[234:235]
	global_load_dwordx4 v[182:185], v[186:187], off nt
	s_nop 0
	global_load_dwordx4 v[186:189], v[186:187], off offset:2048 nt
	s_waitcnt vmcnt(31)
	ds_write_b128 v18, v[30:33]
	s_waitcnt vmcnt(30)
	ds_write_b128 v17, v[34:37]
	s_waitcnt vmcnt(29)
	ds_write_b128 v16, v[38:41]
	s_waitcnt vmcnt(28)
	ds_write_b128 v15, v[42:45]
	s_waitcnt vmcnt(27)
	ds_write_b128 v14, v[46:49]
	s_waitcnt vmcnt(26)
	ds_write_b128 v13, v[50:53]
	s_waitcnt vmcnt(25)
	ds_write_b128 v12, v[54:57]
	s_waitcnt vmcnt(24)
	ds_write_b128 v11, v[58:61]
	s_waitcnt vmcnt(23)
	ds_write_b128 v3, v[62:65]
	s_waitcnt vmcnt(22)
	ds_write_b128 v4, v[66:69]
	s_waitcnt vmcnt(21)
	ds_write_b128 v5, v[70:73]
	s_waitcnt vmcnt(20)
	ds_write_b128 v6, v[74:77]
	s_waitcnt vmcnt(19)
	ds_write_b128 v7, v[78:81]
	s_waitcnt vmcnt(18)
	ds_write_b128 v8, v[82:85]
	s_waitcnt vmcnt(17)
	ds_write_b128 v9, v[86:89]
	s_waitcnt vmcnt(16)
	ds_write_b128 v10, v[90:93]
	s_waitcnt lgkmcnt(0)
	s_barrier
	ds_read_b128 v[30:33], v29
	ds_read_b128 v[34:37], v29 offset:64
	s_waitcnt lgkmcnt(1)
	v_mfma_f32_16x16x32_bf16 v[30:33], v[30:33], v[122:125], 0
	ds_read_b128 v[38:41], v29 offset:8512
	ds_read_b128 v[42:45], v29 offset:16960
	ds_read_b128 v[46:49], v29 offset:25408
	s_waitcnt lgkmcnt(3)
	v_mfma_f32_16x16x32_bf16 v[30:33], v[34:37], v[118:121], v[30:33]
	ds_read_b128 v[34:37], v29 offset:128
	ds_read_b128 v[50:53], v29 offset:33856
	ds_read_b128 v[54:57], v29 offset:42304
	s_waitcnt lgkmcnt(2)
	v_mfma_f32_16x16x32_bf16 v[30:33], v[34:37], v[114:117], v[30:33]
	ds_read_b128 v[34:37], v29 offset:192
	ds_read_b128 v[58:61], v29 offset:50752
	ds_read_b128 v[62:65], v29 offset:59200
	s_waitcnt lgkmcnt(2)
	v_mfma_f32_16x16x32_bf16 v[30:33], v[34:37], v[110:113], v[30:33]
	ds_read_b128 v[34:37], v29 offset:256
	s_waitcnt lgkmcnt(0)
	v_mfma_f32_16x16x32_bf16 v[30:33], v[34:37], v[106:109], v[30:33]
	ds_read_b128 v[34:37], v29 offset:320
	s_waitcnt lgkmcnt(0)
	v_mfma_f32_16x16x32_bf16 v[30:33], v[34:37], v[102:105], v[30:33]
	ds_read_b128 v[34:37], v29 offset:384
	s_waitcnt lgkmcnt(0)
	v_mfma_f32_16x16x32_bf16 v[30:33], v[34:37], v[98:101], v[30:33]
	ds_read_b128 v[34:37], v29 offset:448
	s_waitcnt lgkmcnt(0)
	v_mfma_f32_16x16x32_bf16 v[30:33], v[34:37], v[94:97], v[30:33]
	ds_read_b128 v[34:37], v29 offset:8448
	s_waitcnt lgkmcnt(0)
	v_mfma_f32_16x16x32_bf16 v[34:37], v[34:37], v[122:125], 0
	v_mfma_f32_16x16x32_bf16 v[34:37], v[38:41], v[118:121], v[34:37]
	ds_read_b128 v[38:41], v29 offset:8576
	s_waitcnt lgkmcnt(0)
	v_mfma_f32_16x16x32_bf16 v[34:37], v[38:41], v[114:117], v[34:37]
	ds_read_b128 v[38:41], v29 offset:8640
	s_waitcnt lgkmcnt(0)
	v_mfma_f32_16x16x32_bf16 v[34:37], v[38:41], v[110:113], v[34:37]
	ds_read_b128 v[38:41], v29 offset:8704
	s_waitcnt lgkmcnt(0)
	v_mfma_f32_16x16x32_bf16 v[34:37], v[38:41], v[106:109], v[34:37]
	ds_read_b128 v[38:41], v29 offset:8768
	s_waitcnt lgkmcnt(0)
	v_mfma_f32_16x16x32_bf16 v[34:37], v[38:41], v[102:105], v[34:37]
	ds_read_b128 v[38:41], v29 offset:8832
	s_waitcnt lgkmcnt(0)
	v_mfma_f32_16x16x32_bf16 v[34:37], v[38:41], v[98:101], v[34:37]
	ds_read_b128 v[38:41], v29 offset:8896
	s_waitcnt lgkmcnt(0)
	v_mfma_f32_16x16x32_bf16 v[34:37], v[38:41], v[94:97], v[34:37]
	ds_read_b128 v[38:41], v29 offset:16896
	s_waitcnt lgkmcnt(0)
	v_mfma_f32_16x16x32_bf16 v[38:41], v[38:41], v[122:125], 0
	v_mfma_f32_16x16x32_bf16 v[38:41], v[42:45], v[118:121], v[38:41]
	ds_read_b128 v[42:45], v29 offset:17024
	s_waitcnt lgkmcnt(0)
	v_mfma_f32_16x16x32_bf16 v[38:41], v[42:45], v[114:117], v[38:41]
	ds_read_b128 v[42:45], v29 offset:17088
	s_waitcnt lgkmcnt(0)
	v_mfma_f32_16x16x32_bf16 v[38:41], v[42:45], v[110:113], v[38:41]
	ds_read_b128 v[42:45], v29 offset:17152
	s_waitcnt lgkmcnt(0)
	v_mfma_f32_16x16x32_bf16 v[38:41], v[42:45], v[106:109], v[38:41]
	ds_read_b128 v[42:45], v29 offset:17216
	s_waitcnt lgkmcnt(0)
	v_mfma_f32_16x16x32_bf16 v[38:41], v[42:45], v[102:105], v[38:41]
	ds_read_b128 v[42:45], v29 offset:17280
	s_waitcnt lgkmcnt(0)
	v_mfma_f32_16x16x32_bf16 v[38:41], v[42:45], v[98:101], v[38:41]
	ds_read_b128 v[42:45], v29 offset:17344
	s_waitcnt lgkmcnt(0)
	v_mfma_f32_16x16x32_bf16 v[38:41], v[42:45], v[94:97], v[38:41]
	ds_read_b128 v[42:45], v29 offset:25344
	s_waitcnt lgkmcnt(0)
	v_mfma_f32_16x16x32_bf16 v[42:45], v[42:45], v[122:125], 0
	v_mfma_f32_16x16x32_bf16 v[42:45], v[46:49], v[118:121], v[42:45]
	ds_read_b128 v[46:49], v29 offset:25472
	s_waitcnt lgkmcnt(0)
	v_mfma_f32_16x16x32_bf16 v[42:45], v[46:49], v[114:117], v[42:45]
	ds_read_b128 v[46:49], v29 offset:25536
	s_waitcnt lgkmcnt(0)
	v_mfma_f32_16x16x32_bf16 v[42:45], v[46:49], v[110:113], v[42:45]
	ds_read_b128 v[46:49], v29 offset:25600
	s_waitcnt lgkmcnt(0)
	v_mfma_f32_16x16x32_bf16 v[42:45], v[46:49], v[106:109], v[42:45]
	ds_read_b128 v[46:49], v29 offset:25664
	s_waitcnt lgkmcnt(0)
	v_mfma_f32_16x16x32_bf16 v[42:45], v[46:49], v[102:105], v[42:45]
	ds_read_b128 v[46:49], v29 offset:25728
	s_waitcnt lgkmcnt(0)
	v_mfma_f32_16x16x32_bf16 v[42:45], v[46:49], v[98:101], v[42:45]
	ds_read_b128 v[46:49], v29 offset:25792
	s_waitcnt lgkmcnt(0)
	v_mfma_f32_16x16x32_bf16 v[42:45], v[46:49], v[94:97], v[42:45]
	ds_read_b128 v[46:49], v29 offset:33792
	s_waitcnt lgkmcnt(0)
	v_mfma_f32_16x16x32_bf16 v[46:49], v[46:49], v[122:125], 0
	v_mfma_f32_16x16x32_bf16 v[46:49], v[50:53], v[118:121], v[46:49]
	ds_read_b128 v[50:53], v29 offset:33920
	s_waitcnt lgkmcnt(0)
	v_mfma_f32_16x16x32_bf16 v[46:49], v[50:53], v[114:117], v[46:49]
	ds_read_b128 v[50:53], v29 offset:33984
	s_waitcnt lgkmcnt(0)
	v_mfma_f32_16x16x32_bf16 v[46:49], v[50:53], v[110:113], v[46:49]
	ds_read_b128 v[50:53], v29 offset:34048
	s_waitcnt lgkmcnt(0)
	v_mfma_f32_16x16x32_bf16 v[46:49], v[50:53], v[106:109], v[46:49]
	ds_read_b128 v[50:53], v29 offset:34112
	s_waitcnt lgkmcnt(0)
	v_mfma_f32_16x16x32_bf16 v[46:49], v[50:53], v[102:105], v[46:49]
	ds_read_b128 v[50:53], v29 offset:34176
	s_waitcnt lgkmcnt(0)
	v_mfma_f32_16x16x32_bf16 v[46:49], v[50:53], v[98:101], v[46:49]
	ds_read_b128 v[50:53], v29 offset:34240
	s_waitcnt lgkmcnt(0)
	v_mfma_f32_16x16x32_bf16 v[46:49], v[50:53], v[94:97], v[46:49]
	ds_read_b128 v[50:53], v29 offset:42240
	s_waitcnt lgkmcnt(0)
	v_mfma_f32_16x16x32_bf16 v[50:53], v[50:53], v[122:125], 0
	v_mfma_f32_16x16x32_bf16 v[50:53], v[54:57], v[118:121], v[50:53]
	ds_read_b128 v[54:57], v29 offset:42368
	s_waitcnt lgkmcnt(0)
	v_mfma_f32_16x16x32_bf16 v[50:53], v[54:57], v[114:117], v[50:53]
	ds_read_b128 v[54:57], v29 offset:42432
	s_waitcnt lgkmcnt(0)
	v_mfma_f32_16x16x32_bf16 v[50:53], v[54:57], v[110:113], v[50:53]
	ds_read_b128 v[54:57], v29 offset:42496
	s_waitcnt lgkmcnt(0)
	v_mfma_f32_16x16x32_bf16 v[50:53], v[54:57], v[106:109], v[50:53]
	ds_read_b128 v[54:57], v29 offset:42560
	s_waitcnt lgkmcnt(0)
	v_mfma_f32_16x16x32_bf16 v[50:53], v[54:57], v[102:105], v[50:53]
	ds_read_b128 v[54:57], v29 offset:42624
	s_waitcnt lgkmcnt(0)
	v_mfma_f32_16x16x32_bf16 v[50:53], v[54:57], v[98:101], v[50:53]
	ds_read_b128 v[54:57], v29 offset:42688
	s_waitcnt lgkmcnt(0)
	v_mfma_f32_16x16x32_bf16 v[50:53], v[54:57], v[94:97], v[50:53]
	ds_read_b128 v[54:57], v29 offset:50688
	s_waitcnt lgkmcnt(0)
	v_mfma_f32_16x16x32_bf16 v[54:57], v[54:57], v[122:125], 0
	v_mfma_f32_16x16x32_bf16 v[54:57], v[58:61], v[118:121], v[54:57]
	ds_read_b128 v[58:61], v29 offset:50816
	s_waitcnt lgkmcnt(0)
	v_mfma_f32_16x16x32_bf16 v[54:57], v[58:61], v[114:117], v[54:57]
	ds_read_b128 v[58:61], v29 offset:50880
	s_waitcnt lgkmcnt(0)
	v_mfma_f32_16x16x32_bf16 v[54:57], v[58:61], v[110:113], v[54:57]
	ds_read_b128 v[58:61], v29 offset:50944
	s_waitcnt lgkmcnt(0)
	v_mfma_f32_16x16x32_bf16 v[54:57], v[58:61], v[106:109], v[54:57]
	ds_read_b128 v[58:61], v29 offset:51008
	s_waitcnt lgkmcnt(0)
	v_mfma_f32_16x16x32_bf16 v[54:57], v[58:61], v[102:105], v[54:57]
	ds_read_b128 v[58:61], v29 offset:51072
	s_waitcnt lgkmcnt(0)
	v_mfma_f32_16x16x32_bf16 v[54:57], v[58:61], v[98:101], v[54:57]
	ds_read_b128 v[58:61], v29 offset:51136
	s_waitcnt lgkmcnt(0)
	v_mfma_f32_16x16x32_bf16 v[54:57], v[58:61], v[94:97], v[54:57]
	ds_read_b128 v[58:61], v29 offset:59136
	s_waitcnt lgkmcnt(0)
	v_mfma_f32_16x16x32_bf16 v[58:61], v[58:61], v[122:125], 0
	v_mfma_f32_16x16x32_bf16 v[58:61], v[62:65], v[118:121], v[58:61]
	ds_read_b128 v[62:65], v29 offset:59264
	s_waitcnt lgkmcnt(0)
	v_mfma_f32_16x16x32_bf16 v[58:61], v[62:65], v[114:117], v[58:61]
	ds_read_b128 v[62:65], v29 offset:59328
	s_waitcnt lgkmcnt(0)
	v_mfma_f32_16x16x32_bf16 v[58:61], v[62:65], v[110:113], v[58:61]
	ds_read_b128 v[62:65], v29 offset:59392
	s_waitcnt lgkmcnt(0)
	v_mfma_f32_16x16x32_bf16 v[58:61], v[62:65], v[106:109], v[58:61]
	ds_read_b128 v[62:65], v29 offset:59456
	s_waitcnt lgkmcnt(0)
	v_mfma_f32_16x16x32_bf16 v[58:61], v[62:65], v[102:105], v[58:61]
	ds_read_b128 v[62:65], v29 offset:59520
	s_waitcnt lgkmcnt(0)
	v_mfma_f32_16x16x32_bf16 v[58:61], v[62:65], v[98:101], v[58:61]
	ds_read_b128 v[62:65], v29 offset:59584
	s_waitcnt lgkmcnt(0)
	v_mfma_f32_16x16x32_bf16 v[58:61], v[62:65], v[94:97], v[58:61]
	ds_read_b128 v[62:65], v20
	v_add_u32_e32 v20, 0x10840, v29
	ds_read_b128 v[66:69], v20
	s_waitcnt lgkmcnt(1)
	v_mfma_f32_16x16x32_bf16 v[62:65], v[62:65], v[122:125], 0
	v_add_u32_e32 v20, 0x10880, v29
	s_waitcnt lgkmcnt(0)
	v_mfma_f32_16x16x32_bf16 v[62:65], v[66:69], v[118:121], v[62:65]
	ds_read_b128 v[66:69], v20
	v_add_u32_e32 v20, 0x108c0, v29
	s_waitcnt lgkmcnt(0)
	v_mfma_f32_16x16x32_bf16 v[62:65], v[66:69], v[114:117], v[62:65]
	ds_read_b128 v[66:69], v20
	v_add_u32_e32 v20, 0x10900, v29
	s_waitcnt lgkmcnt(0)
	v_mfma_f32_16x16x32_bf16 v[62:65], v[66:69], v[110:113], v[62:65]
	ds_read_b128 v[66:69], v20
	v_add_u32_e32 v20, 0x10940, v29
	s_waitcnt lgkmcnt(0)
	v_mfma_f32_16x16x32_bf16 v[62:65], v[66:69], v[106:109], v[62:65]
	ds_read_b128 v[66:69], v20
	v_add_u32_e32 v20, 0x10980, v29
	s_waitcnt lgkmcnt(0)
	v_mfma_f32_16x16x32_bf16 v[62:65], v[66:69], v[102:105], v[62:65]
	ds_read_b128 v[66:69], v20
	v_add_u32_e32 v20, 0x109c0, v29
	s_waitcnt lgkmcnt(0)
	v_mfma_f32_16x16x32_bf16 v[62:65], v[66:69], v[98:101], v[62:65]
	ds_read_b128 v[66:69], v20
	v_add_u32_e32 v20, 0x12900, v29
	s_waitcnt lgkmcnt(0)
	v_mfma_f32_16x16x32_bf16 v[190:193], v[66:69], v[94:97], v[62:65]
	s_nop 3
	ds_read_b128 v[62:65], v20
	v_add_u32_e32 v20, 0x12940, v29
	ds_read_b128 v[66:69], v20
	s_waitcnt lgkmcnt(1)
	v_mfma_f32_16x16x32_bf16 v[62:65], v[62:65], v[122:125], 0
	v_add_u32_e32 v20, 0x12980, v29
	s_waitcnt lgkmcnt(0)
	v_mfma_f32_16x16x32_bf16 v[62:65], v[66:69], v[118:121], v[62:65]
	ds_read_b128 v[66:69], v20
	v_add_u32_e32 v20, 0x129c0, v29
	s_waitcnt lgkmcnt(0)
	v_mfma_f32_16x16x32_bf16 v[62:65], v[66:69], v[114:117], v[62:65]
	ds_read_b128 v[66:69], v20
	v_add_u32_e32 v20, 0x12a00, v29
	s_waitcnt lgkmcnt(0)
	v_mfma_f32_16x16x32_bf16 v[62:65], v[66:69], v[110:113], v[62:65]
	ds_read_b128 v[66:69], v20
	v_add_u32_e32 v20, 0x12a40, v29
	s_waitcnt lgkmcnt(0)
	v_mfma_f32_16x16x32_bf16 v[62:65], v[66:69], v[106:109], v[62:65]
	ds_read_b128 v[66:69], v20
	v_add_u32_e32 v20, 0x12a80, v29
	s_waitcnt lgkmcnt(0)
	v_mfma_f32_16x16x32_bf16 v[62:65], v[66:69], v[102:105], v[62:65]
	ds_read_b128 v[66:69], v20
	v_add_u32_e32 v20, 0x12ac0, v29
	s_waitcnt lgkmcnt(0)
	v_mfma_f32_16x16x32_bf16 v[62:65], v[66:69], v[98:101], v[62:65]
	ds_read_b128 v[66:69], v20
	v_add_u32_e32 v20, 0x14a00, v29
	s_waitcnt lgkmcnt(0)
	v_mfma_f32_16x16x32_bf16 v[194:197], v[66:69], v[94:97], v[62:65]
	s_nop 3
	ds_read_b128 v[62:65], v20
	v_add_u32_e32 v20, 0x14a40, v29
	ds_read_b128 v[66:69], v20
	s_waitcnt lgkmcnt(1)
	v_mfma_f32_16x16x32_bf16 v[62:65], v[62:65], v[122:125], 0
	v_add_u32_e32 v20, 0x14a80, v29
	s_waitcnt lgkmcnt(0)
	v_mfma_f32_16x16x32_bf16 v[62:65], v[66:69], v[118:121], v[62:65]
	ds_read_b128 v[66:69], v20
	v_add_u32_e32 v20, 0x14ac0, v29
	s_waitcnt lgkmcnt(0)
	v_mfma_f32_16x16x32_bf16 v[62:65], v[66:69], v[114:117], v[62:65]
	ds_read_b128 v[66:69], v20
	v_add_u32_e32 v20, 0x14b00, v29
	s_waitcnt lgkmcnt(0)
	v_mfma_f32_16x16x32_bf16 v[62:65], v[66:69], v[110:113], v[62:65]
	ds_read_b128 v[66:69], v20
	v_add_u32_e32 v20, 0x14b40, v29
	s_waitcnt lgkmcnt(0)
	v_mfma_f32_16x16x32_bf16 v[62:65], v[66:69], v[106:109], v[62:65]
	ds_read_b128 v[66:69], v20
	v_add_u32_e32 v20, 0x14b80, v29
	s_waitcnt lgkmcnt(0)
	v_mfma_f32_16x16x32_bf16 v[62:65], v[66:69], v[102:105], v[62:65]
	ds_read_b128 v[66:69], v20
	v_add_u32_e32 v20, 0x14bc0, v29
	s_waitcnt lgkmcnt(0)
	v_mfma_f32_16x16x32_bf16 v[62:65], v[66:69], v[98:101], v[62:65]
	ds_read_b128 v[66:69], v20
	v_add_u32_e32 v20, 0x16b00, v29
	s_waitcnt lgkmcnt(0)
	v_mfma_f32_16x16x32_bf16 v[198:201], v[66:69], v[94:97], v[62:65]
	s_nop 3
	ds_read_b128 v[62:65], v20
	v_add_u32_e32 v20, 0x16b40, v29
	ds_read_b128 v[66:69], v20
	s_waitcnt lgkmcnt(1)
	v_mfma_f32_16x16x32_bf16 v[62:65], v[62:65], v[122:125], 0
	v_add_u32_e32 v20, 0x16b80, v29
	s_waitcnt lgkmcnt(0)
	v_mfma_f32_16x16x32_bf16 v[62:65], v[66:69], v[118:121], v[62:65]
	ds_read_b128 v[66:69], v20
	v_add_u32_e32 v20, 0x16bc0, v29
	s_waitcnt lgkmcnt(0)
	v_mfma_f32_16x16x32_bf16 v[62:65], v[66:69], v[114:117], v[62:65]
	ds_read_b128 v[66:69], v20
	v_add_u32_e32 v20, 0x16c00, v29
	s_waitcnt lgkmcnt(0)
	v_mfma_f32_16x16x32_bf16 v[62:65], v[66:69], v[110:113], v[62:65]
	ds_read_b128 v[66:69], v20
	v_add_u32_e32 v20, 0x16c40, v29
	s_waitcnt lgkmcnt(0)
	v_mfma_f32_16x16x32_bf16 v[62:65], v[66:69], v[106:109], v[62:65]
	ds_read_b128 v[66:69], v20
	v_add_u32_e32 v20, 0x16c80, v29
	s_waitcnt lgkmcnt(0)
	v_mfma_f32_16x16x32_bf16 v[62:65], v[66:69], v[102:105], v[62:65]
	ds_read_b128 v[66:69], v20
	v_add_u32_e32 v20, 0x16cc0, v29
	s_waitcnt lgkmcnt(0)
	v_mfma_f32_16x16x32_bf16 v[62:65], v[66:69], v[98:101], v[62:65]
	ds_read_b128 v[66:69], v20
	v_add_u32_e32 v20, 0x18c00, v29
	s_waitcnt lgkmcnt(0)
	v_mfma_f32_16x16x32_bf16 v[202:205], v[66:69], v[94:97], v[62:65]
	s_nop 3
	ds_read_b128 v[62:65], v20
	v_add_u32_e32 v20, 0x18c40, v29
	ds_read_b128 v[66:69], v20
	s_waitcnt lgkmcnt(1)
	v_mfma_f32_16x16x32_bf16 v[62:65], v[62:65], v[122:125], 0
	v_add_u32_e32 v20, 0x18c80, v29
	s_waitcnt lgkmcnt(0)
	v_mfma_f32_16x16x32_bf16 v[62:65], v[66:69], v[118:121], v[62:65]
	ds_read_b128 v[66:69], v20
	v_add_u32_e32 v20, 0x18cc0, v29
	s_waitcnt lgkmcnt(0)
	v_mfma_f32_16x16x32_bf16 v[62:65], v[66:69], v[114:117], v[62:65]
	ds_read_b128 v[66:69], v20
	v_add_u32_e32 v20, 0x18d00, v29
	s_waitcnt lgkmcnt(0)
	v_mfma_f32_16x16x32_bf16 v[62:65], v[66:69], v[110:113], v[62:65]
	ds_read_b128 v[66:69], v20
	v_add_u32_e32 v20, 0x18d40, v29
	s_waitcnt lgkmcnt(0)
	v_mfma_f32_16x16x32_bf16 v[62:65], v[66:69], v[106:109], v[62:65]
	ds_read_b128 v[66:69], v20
	v_add_u32_e32 v20, 0x18d80, v29
	s_waitcnt lgkmcnt(0)
	v_mfma_f32_16x16x32_bf16 v[62:65], v[66:69], v[102:105], v[62:65]
	ds_read_b128 v[66:69], v20
	v_add_u32_e32 v20, 0x18dc0, v29
	s_waitcnt lgkmcnt(0)
	v_mfma_f32_16x16x32_bf16 v[62:65], v[66:69], v[98:101], v[62:65]
	ds_read_b128 v[66:69], v20
	v_add_u32_e32 v20, 0x1ad00, v29
	s_waitcnt lgkmcnt(0)
	v_mfma_f32_16x16x32_bf16 v[206:209], v[66:69], v[94:97], v[62:65]
	s_nop 3
	ds_read_b128 v[62:65], v20
	v_add_u32_e32 v20, 0x1ad40, v29
	ds_read_b128 v[66:69], v20
	s_waitcnt lgkmcnt(1)
	v_mfma_f32_16x16x32_bf16 v[62:65], v[62:65], v[122:125], 0
	v_add_u32_e32 v20, 0x1ad80, v29
	s_waitcnt lgkmcnt(0)
	v_mfma_f32_16x16x32_bf16 v[62:65], v[66:69], v[118:121], v[62:65]
	ds_read_b128 v[66:69], v20
	v_add_u32_e32 v20, 0x1adc0, v29
	s_waitcnt lgkmcnt(0)
	v_mfma_f32_16x16x32_bf16 v[62:65], v[66:69], v[114:117], v[62:65]
	ds_read_b128 v[66:69], v20
	v_add_u32_e32 v20, 0x1ae00, v29
	s_waitcnt lgkmcnt(0)
	v_mfma_f32_16x16x32_bf16 v[62:65], v[66:69], v[110:113], v[62:65]
	ds_read_b128 v[66:69], v20
	v_add_u32_e32 v20, 0x1ae40, v29
	s_waitcnt lgkmcnt(0)
	v_mfma_f32_16x16x32_bf16 v[62:65], v[66:69], v[106:109], v[62:65]
	ds_read_b128 v[66:69], v20
	v_add_u32_e32 v20, 0x1ae80, v29
	s_waitcnt lgkmcnt(0)
	v_mfma_f32_16x16x32_bf16 v[62:65], v[66:69], v[102:105], v[62:65]
	ds_read_b128 v[66:69], v20
	v_add_u32_e32 v20, 0x1aec0, v29
	s_waitcnt lgkmcnt(0)
	v_mfma_f32_16x16x32_bf16 v[62:65], v[66:69], v[98:101], v[62:65]
	ds_read_b128 v[66:69], v20
	v_add_u32_e32 v20, 0x1ce00, v29
	s_waitcnt lgkmcnt(0)
	v_mfma_f32_16x16x32_bf16 v[210:213], v[66:69], v[94:97], v[62:65]
	s_nop 3
	ds_read_b128 v[62:65], v20
	v_add_u32_e32 v20, 0x1ce40, v29
	ds_read_b128 v[66:69], v20
	s_waitcnt lgkmcnt(1)
	v_mfma_f32_16x16x32_bf16 v[62:65], v[62:65], v[122:125], 0
	v_add_u32_e32 v20, 0x1ce80, v29
	s_waitcnt lgkmcnt(0)
	v_mfma_f32_16x16x32_bf16 v[62:65], v[66:69], v[118:121], v[62:65]
	ds_read_b128 v[66:69], v20
	v_add_u32_e32 v20, 0x1cec0, v29
	s_waitcnt lgkmcnt(0)
	v_mfma_f32_16x16x32_bf16 v[62:65], v[66:69], v[114:117], v[62:65]
	ds_read_b128 v[66:69], v20
	v_add_u32_e32 v20, 0x1cf00, v29
	s_waitcnt lgkmcnt(0)
	v_mfma_f32_16x16x32_bf16 v[62:65], v[66:69], v[110:113], v[62:65]
	ds_read_b128 v[66:69], v20
	v_add_u32_e32 v20, 0x1cf40, v29
	s_waitcnt lgkmcnt(0)
	v_mfma_f32_16x16x32_bf16 v[62:65], v[66:69], v[106:109], v[62:65]
	ds_read_b128 v[66:69], v20
	v_add_u32_e32 v20, 0x1cf80, v29
	s_waitcnt lgkmcnt(0)
	v_mfma_f32_16x16x32_bf16 v[62:65], v[66:69], v[102:105], v[62:65]
	ds_read_b128 v[66:69], v20
	v_add_u32_e32 v20, 0x1cfc0, v29
	s_waitcnt lgkmcnt(0)
	v_mfma_f32_16x16x32_bf16 v[62:65], v[66:69], v[98:101], v[62:65]
	ds_read_b128 v[66:69], v20
	v_add_u32_e32 v20, 0x1ef00, v29
	s_waitcnt lgkmcnt(0)
	v_mfma_f32_16x16x32_bf16 v[214:217], v[66:69], v[94:97], v[62:65]
	s_nop 3
	ds_read_b128 v[62:65], v20
	v_add_u32_e32 v20, 0x1ef40, v29
	ds_read_b128 v[66:69], v20
	s_waitcnt lgkmcnt(1)
	v_mfma_f32_16x16x32_bf16 v[62:65], v[62:65], v[122:125], 0
	v_add_u32_e32 v20, 0x1ef80, v29
	s_waitcnt lgkmcnt(0)
	v_mfma_f32_16x16x32_bf16 v[62:65], v[66:69], v[118:121], v[62:65]
	ds_read_b128 v[66:69], v20
	v_add_u32_e32 v20, 0x1efc0, v29
	s_waitcnt lgkmcnt(0)
	v_mfma_f32_16x16x32_bf16 v[62:65], v[66:69], v[114:117], v[62:65]
	ds_read_b128 v[66:69], v20
	v_add_u32_e32 v20, 0x1f000, v29
	s_waitcnt lgkmcnt(0)
	v_mfma_f32_16x16x32_bf16 v[62:65], v[66:69], v[110:113], v[62:65]
	ds_read_b128 v[66:69], v20
	v_add_u32_e32 v20, 0x1f040, v29
	s_waitcnt lgkmcnt(0)
	v_mfma_f32_16x16x32_bf16 v[62:65], v[66:69], v[106:109], v[62:65]
	ds_read_b128 v[66:69], v20
	v_add_u32_e32 v20, 0x1f080, v29
	s_waitcnt lgkmcnt(0)
	v_mfma_f32_16x16x32_bf16 v[62:65], v[66:69], v[102:105], v[62:65]
	ds_read_b128 v[66:69], v20
	v_add_u32_e32 v20, 0x1f0c0, v29
	s_waitcnt lgkmcnt(0)
	v_mfma_f32_16x16x32_bf16 v[62:65], v[66:69], v[98:101], v[62:65]
	ds_read_b128 v[66:69], v20
	v_add_u32_e32 v20, 1, v233
	v_cvt_f32_i32_e32 v20, v20
	s_waitcnt lgkmcnt(0)
	v_mfma_f32_16x16x32_bf16 v[218:221], v[66:69], v[94:97], v[62:65]
	v_mul_f32_e32 v20, v237, v20
	v_exp_f32_e32 v20, v20
	s_barrier
	v_pk_mul_f32 v[92:93], v[20:21], v[32:33] op_sel_hi:[0,1]
	v_pk_mul_f32 v[90:91], v[20:21], v[30:31] op_sel_hi:[0,1]
	v_pk_mul_f32 v[88:89], v[20:21], v[36:37] op_sel_hi:[0,1]
	v_pk_mul_f32 v[86:87], v[20:21], v[34:35] op_sel_hi:[0,1]
	v_pk_mul_f32 v[84:85], v[20:21], v[40:41] op_sel_hi:[0,1]
	v_pk_mul_f32 v[82:83], v[20:21], v[38:39] op_sel_hi:[0,1]
	v_pk_mul_f32 v[80:81], v[20:21], v[44:45] op_sel_hi:[0,1]
	v_pk_mul_f32 v[78:79], v[20:21], v[42:43] op_sel_hi:[0,1]
	v_pk_mul_f32 v[76:77], v[20:21], v[48:49] op_sel_hi:[0,1]
	v_pk_mul_f32 v[74:75], v[20:21], v[46:47] op_sel_hi:[0,1]
	v_pk_mul_f32 v[72:73], v[20:21], v[52:53] op_sel_hi:[0,1]
	v_pk_mul_f32 v[70:71], v[20:21], v[50:51] op_sel_hi:[0,1]
	v_pk_mul_f32 v[68:69], v[20:21], v[56:57] op_sel_hi:[0,1]
	v_pk_mul_f32 v[66:67], v[20:21], v[54:55] op_sel_hi:[0,1]
	v_pk_mul_f32 v[64:65], v[20:21], v[60:61] op_sel_hi:[0,1]
	v_pk_mul_f32 v[62:63], v[20:21], v[58:59] op_sel_hi:[0,1]
	v_pk_mul_f32 v[60:61], v[20:21], v[192:193] op_sel_hi:[0,1]
	v_pk_mul_f32 v[58:59], v[20:21], v[190:191] op_sel_hi:[0,1]
	v_pk_mul_f32 v[56:57], v[20:21], v[196:197] op_sel_hi:[0,1]
	v_pk_mul_f32 v[54:55], v[20:21], v[194:195] op_sel_hi:[0,1]
	v_pk_mul_f32 v[52:53], v[20:21], v[200:201] op_sel_hi:[0,1]
	v_pk_mul_f32 v[50:51], v[20:21], v[198:199] op_sel_hi:[0,1]
	v_pk_mul_f32 v[48:49], v[20:21], v[204:205] op_sel_hi:[0,1]
	v_pk_mul_f32 v[46:47], v[20:21], v[202:203] op_sel_hi:[0,1]
	v_pk_mul_f32 v[44:45], v[20:21], v[208:209] op_sel_hi:[0,1]
	v_pk_mul_f32 v[42:43], v[20:21], v[206:207] op_sel_hi:[0,1]
	v_pk_mul_f32 v[40:41], v[20:21], v[212:213] op_sel_hi:[0,1]
	v_pk_mul_f32 v[38:39], v[20:21], v[210:211] op_sel_hi:[0,1]
	v_pk_mul_f32 v[36:37], v[20:21], v[216:217] op_sel_hi:[0,1]
	v_pk_mul_f32 v[34:35], v[20:21], v[214:215] op_sel_hi:[0,1]
	v_pk_mul_f32 v[32:33], v[20:21], v[220:221] op_sel_hi:[0,1]
	v_pk_mul_f32 v[30:31], v[20:21], v[218:219] op_sel_hi:[0,1]
	s_branch .LBB0_1070
